# bundle3 with wait-state fix: E-j + GU-tail MFMA slot split + resid-epilogue load hoist (s_nop kept for store-data WAR) + FFT1 twiddle batch + FFT2 DT-load batch + redundant lgkmcnt waits removed + nt
# speedup vs baseline: 1.0082x; 1.0082x over previous
; __device__ __forceinline__ unsigned cvt_pk_bf16(float lo, float hi) { unsigned r; asm volatile("v_cvt_pk_bf16_f32 %0, %1, %2" : "=v"(r) : "v"(lo), "v"(hi)); return r; }
;     __device__ __forceinline__ void operator()(const f32x4 (&acc)[2][2][4][2], const Unit& u, int wr, int wc, int fr, int fq) const {
;     ...
;             for (int m = 0; m < 4; ++m) { const int row = row0 + ai * HALF + m * 16; const size_t off = (size_t)row * 2048 + col0; float sq = 0.f;
; #pragma unroll
;                 for (int bj = 0; bj < 2; ++bj) { const u32x4 r = rb[m][bj];
;                     const f32x4 b0 = (f32x4){__builtin_bit_cast(float, r.x << 16), __builtin_bit_cast(float, r.x & 0xffff0000u), __builtin_bit_cast(float, r.y << 16), __builtin_bit_cast(float, r.y & 0xffff0000u)};
;                     const f32x4 b1 = (f32x4){__builtin_bit_cast(float, r.z << 16), __builtin_bit_cast(float, r.z & 0xffff0000u), __builtin_bit_cast(float, r.w << 16), __builtin_bit_cast(float, r.w & 0xffff0000u)};
;                     const f32x4 o0 = b0 + acc[ai][bj][m][0] * alpha, o1 = b1 + acc[ai][bj][m][1] * alpha;
;                     if (wf) { *(f32x4*)(fout + off + bj * HALF) = o0; *(f32x4*)(fout + off + bj * HALF + 4) = o1; }
;                     sq += (o0[0] * o0[0] + o0[1] * o0[1]) + (o0[2] * o0[2] + o0[3] * o0[3]) + (o1[0] * o1[0] + o1[1] * o1[1]) + (o1[2] * o1[2] + o1[3] * o1[3]);
;                     u32x4 w; w.x = cvt_pk_bf16(o0[0], o0[1]); w.y = cvt_pk_bf16(o0[2], o0[3]); w.z = cvt_pk_bf16(o1[0], o1[1]); w.w = cvt_pk_bf16(o1[2], o1[3]);
;                     *(u32x4*)(xb + off + bj * HALF) = w; }
.LBB0_305:
	v_cvt_pk_bf16_f32 v104, v60, v61
	v_cvt_pk_bf16_f32 v105, v62, v63
	v_cvt_pk_bf16_f32 v106, v56, v57
	v_cvt_pk_bf16_f32 v107, v58, v59
	v_lshl_add_u64 v[100:101], v[100:101], 1, v[168:169]
	global_store_dwordx4 v[100:101], v[104:107], off
	s_and_b64 vcc, exec, s[10:11]
	s_nop 0
	v_lshlrev_b32_e32 v104, 16, v204
	v_and_b32_e32 v105, 0xffff0000, v204
	v_lshlrev_b32_e32 v88, 16, v205
	v_and_b32_e32 v89, 0xffff0000, v205
	v_lshlrev_b32_e32 v106, 16, v206
	v_and_b32_e32 v107, 0xffff0000, v206
	v_lshlrev_b32_e32 v90, 16, v207
	v_and_b32_e32 v91, 0xffff0000, v207
	v_pk_fma_f32 v[54:55], v[54:55], 0.5, v[88:89] op_sel_hi:[1,0,1]
	v_pk_fma_f32 v[52:53], v[52:53], 0.5, v[104:105] op_sel_hi:[1,0,1]
	v_pk_fma_f32 v[50:51], v[50:51], 0.5, v[90:91] op_sel_hi:[1,0,1]
	v_pk_fma_f32 v[48:49], v[48:49], 0.5, v[106:107] op_sel_hi:[1,0,1]
	s_cbranch_vccnz .LBB0_307
	global_store_dwordx4 v[102:103], v[52:55], off offset:512
	global_store_dwordx4 v[102:103], v[48:51], off offset:528

; __device__ __forceinline__ unsigned cvt_pk_bf16(float lo, float hi) { unsigned r; asm volatile("v_cvt_pk_bf16_f32 %0, %1, %2" : "=v"(r) : "v"(lo), "v"(hi)); return r; }
;     __device__ __forceinline__ void operator()(const f32x4 (&acc)[2][2][4][2], const Unit& u, int wr, int wc, int fr, int fq) const {
;     ...
;             for (int m = 0; m < 4; ++m) { const int row = row0 + ai * HALF + m * 16; const size_t off = (size_t)row * 2048 + col0; float sq = 0.f;
; #pragma unroll
;                 for (int bj = 0; bj < 2; ++bj) { const u32x4 r = rb[m][bj];
;                     const f32x4 b0 = (f32x4){__builtin_bit_cast(float, r.x << 16), __builtin_bit_cast(float, r.x & 0xffff0000u), __builtin_bit_cast(float, r.y << 16), __builtin_bit_cast(float, r.y & 0xffff0000u)};
;                     const f32x4 b1 = (f32x4){__builtin_bit_cast(float, r.z << 16), __builtin_bit_cast(float, r.z & 0xffff0000u), __builtin_bit_cast(float, r.w << 16), __builtin_bit_cast(float, r.w & 0xffff0000u)};
;                     const f32x4 o0 = b0 + acc[ai][bj][m][0] * alpha, o1 = b1 + acc[ai][bj][m][1] * alpha;
;                     if (wf) { *(f32x4*)(fout + off + bj * HALF) = o0; *(f32x4*)(fout + off + bj * HALF + 4) = o1; }
;                     sq += (o0[0] * o0[0] + o0[1] * o0[1]) + (o0[2] * o0[2] + o0[3] * o0[3]) + (o1[0] * o1[0] + o1[1] * o1[1]) + (o1[2] * o1[2] + o1[3] * o1[3]);
;                     u32x4 w; w.x = cvt_pk_bf16(o0[0], o0[1]); w.y = cvt_pk_bf16(o0[2], o0[3]); w.z = cvt_pk_bf16(o1[0], o1[1]); w.w = cvt_pk_bf16(o1[2], o1[3]);
;                     *(u32x4*)(xb + off + bj * HALF) = w; }
.LBB0_309:
	s_or_b64 exec, exec, s[30:31]
	v_lshlrev_b64 v[48:49], 11, v[96:97]
	v_lshl_add_u64 v[50:51], v[48:49], 0, v[170:171]
	s_nop 0
	v_lshlrev_b32_e32 v52, 16, v208
	v_and_b32_e32 v53, 0xffff0000, v208
	v_lshlrev_b32_e32 v54, 16, v209
	v_and_b32_e32 v55, 0xffff0000, v209
	v_lshlrev_b32_e32 v56, 16, v210
	v_and_b32_e32 v57, 0xffff0000, v210
	v_lshlrev_b32_e32 v58, 16, v211
	v_and_b32_e32 v59, 0xffff0000, v211
	v_pk_fma_f32 v[46:47], v[46:47], 0.5, v[54:55] op_sel_hi:[1,0,1]
	v_pk_fma_f32 v[44:45], v[44:45], 0.5, v[52:53] op_sel_hi:[1,0,1]
	v_pk_fma_f32 v[42:43], v[42:43], 0.5, v[58:59] op_sel_hi:[1,0,1]
	v_pk_fma_f32 v[40:41], v[40:41], 0.5, v[56:57] op_sel_hi:[1,0,1]
	s_and_b64 vcc, exec, s[10:11]
	v_lshl_add_u64 v[50:51], v[50:51], 2, s[12:13]
	s_cbranch_vccnz .LBB0_311
	global_store_dwordx4 v[50:51], v[44:47], off
	global_store_dwordx4 v[50:51], v[40:43], off offset:16
.LBB0_311:
	v_cvt_pk_bf16_f32 v52, v44, v45
	v_cvt_pk_bf16_f32 v53, v46, v47
	v_cvt_pk_bf16_f32 v54, v40, v41
	v_cvt_pk_bf16_f32 v55, v42, v43
	v_lshl_add_u64 v[48:49], v[48:49], 1, v[168:169]
	global_store_dwordx4 v[48:49], v[52:55], off
	s_nop 0
	v_lshlrev_b32_e32 v56, 16, v214
	v_and_b32_e32 v57, 0xffff0000, v214
	v_lshlrev_b32_e32 v52, 16, v212
	v_and_b32_e32 v53, 0xffff0000, v212
	v_lshlrev_b32_e32 v54, 16, v213
	v_and_b32_e32 v55, 0xffff0000, v213
	v_lshlrev_b32_e32 v58, 16, v215
	v_and_b32_e32 v59, 0xffff0000, v215
	v_pk_fma_f32 v[38:39], v[38:39], 0.5, v[54:55] op_sel_hi:[1,0,1]
	v_pk_fma_f32 v[36:37], v[36:37], 0.5, v[52:53] op_sel_hi:[1,0,1]
	v_pk_fma_f32 v[34:35], v[34:35], 0.5, v[58:59] op_sel_hi:[1,0,1]
	s_and_b64 vcc, exec, s[10:11]
	v_pk_fma_f32 v[32:33], v[32:33], 0.5, v[56:57] op_sel_hi:[1,0,1]
	s_cbranch_vccnz .LBB0_313
	global_store_dwordx4 v[50:51], v[36:39], off offset:512
	global_store_dwordx4 v[50:51], v[32:35], off offset:528

; __device__ __forceinline__ unsigned cvt_pk_bf16(float lo, float hi) { unsigned r; asm volatile("v_cvt_pk_bf16_f32 %0, %1, %2" : "=v"(r) : "v"(lo), "v"(hi)); return r; }
;     __device__ __forceinline__ void operator()(const f32x4 (&acc)[2][2][4][2], const Unit& u, int wr, int wc, int fr, int fq) const {
;     ...
;             for (int m = 0; m < 4; ++m) { const int row = row0 + ai * HALF + m * 16; const size_t off = (size_t)row * 2048 + col0; float sq = 0.f;
; #pragma unroll
;                 for (int bj = 0; bj < 2; ++bj) { const u32x4 r = rb[m][bj];
;                     const f32x4 b0 = (f32x4){__builtin_bit_cast(float, r.x << 16), __builtin_bit_cast(float, r.x & 0xffff0000u), __builtin_bit_cast(float, r.y << 16), __builtin_bit_cast(float, r.y & 0xffff0000u)};
;                     const f32x4 b1 = (f32x4){__builtin_bit_cast(float, r.z << 16), __builtin_bit_cast(float, r.z & 0xffff0000u), __builtin_bit_cast(float, r.w << 16), __builtin_bit_cast(float, r.w & 0xffff0000u)};
;                     const f32x4 o0 = b0 + acc[ai][bj][m][0] * alpha, o1 = b1 + acc[ai][bj][m][1] * alpha;
;                     if (wf) { *(f32x4*)(fout + off + bj * HALF) = o0; *(f32x4*)(fout + off + bj * HALF + 4) = o1; }
;                     sq += (o0[0] * o0[0] + o0[1] * o0[1]) + (o0[2] * o0[2] + o0[3] * o0[3]) + (o1[0] * o1[0] + o1[1] * o1[1]) + (o1[2] * o1[2] + o1[3] * o1[3]);
;                     u32x4 w; w.x = cvt_pk_bf16(o0[0], o0[1]); w.y = cvt_pk_bf16(o0[2], o0[3]); w.z = cvt_pk_bf16(o1[0], o1[1]); w.w = cvt_pk_bf16(o1[2], o1[3]);
;                     *(u32x4*)(xb + off + bj * HALF) = w; }
.LBB0_315:
	s_or_b64 exec, exec, s[30:31]
	v_lshlrev_b64 v[32:33], 11, v[94:95]
	v_lshl_add_u64 v[34:35], v[32:33], 0, v[170:171]
	s_nop 0
	v_lshlrev_b32_e32 v36, 16, v216
	v_and_b32_e32 v37, 0xffff0000, v216
	v_lshlrev_b32_e32 v38, 16, v217
	v_and_b32_e32 v39, 0xffff0000, v217
	v_lshlrev_b32_e32 v40, 16, v218
	v_and_b32_e32 v41, 0xffff0000, v218
	v_lshlrev_b32_e32 v42, 16, v219
	v_and_b32_e32 v43, 0xffff0000, v219
	v_pk_fma_f32 v[30:31], v[30:31], 0.5, v[38:39] op_sel_hi:[1,0,1]
	v_pk_fma_f32 v[28:29], v[28:29], 0.5, v[36:37] op_sel_hi:[1,0,1]
	v_pk_fma_f32 v[26:27], v[26:27], 0.5, v[42:43] op_sel_hi:[1,0,1]
	v_pk_fma_f32 v[24:25], v[24:25], 0.5, v[40:41] op_sel_hi:[1,0,1]
	s_and_b64 vcc, exec, s[10:11]
	v_lshl_add_u64 v[34:35], v[34:35], 2, s[12:13]
	s_cbranch_vccnz .LBB0_317
	global_store_dwordx4 v[34:35], v[28:31], off
	global_store_dwordx4 v[34:35], v[24:27], off offset:16
.LBB0_317:
	v_cvt_pk_bf16_f32 v36, v28, v29
	v_cvt_pk_bf16_f32 v37, v30, v31
	v_cvt_pk_bf16_f32 v38, v24, v25
	v_cvt_pk_bf16_f32 v39, v26, v27
	v_lshl_add_u64 v[32:33], v[32:33], 1, v[168:169]
	global_store_dwordx4 v[32:33], v[36:39], off
	s_nop 0
	v_lshlrev_b32_e32 v40, 16, v224
	v_and_b32_e32 v41, 0xffff0000, v224
	v_lshlrev_b32_e32 v36, 16, v222
	v_and_b32_e32 v37, 0xffff0000, v222
	v_lshlrev_b32_e32 v38, 16, v223
	v_and_b32_e32 v39, 0xffff0000, v223
	v_lshlrev_b32_e32 v42, 16, v225
	v_and_b32_e32 v43, 0xffff0000, v225
	v_pk_fma_f32 v[22:23], v[22:23], 0.5, v[38:39] op_sel_hi:[1,0,1]
	v_pk_fma_f32 v[20:21], v[20:21], 0.5, v[36:37] op_sel_hi:[1,0,1]
	v_pk_fma_f32 v[18:19], v[18:19], 0.5, v[42:43] op_sel_hi:[1,0,1]
	s_and_b64 vcc, exec, s[10:11]
	v_pk_fma_f32 v[16:17], v[16:17], 0.5, v[40:41] op_sel_hi:[1,0,1]
	s_cbranch_vccnz .LBB0_319
	global_store_dwordx4 v[34:35], v[20:23], off offset:512
	global_store_dwordx4 v[34:35], v[16:19], off offset:528

; __device__ __forceinline__ unsigned cvt_pk_bf16(float lo, float hi) { unsigned r; asm volatile("v_cvt_pk_bf16_f32 %0, %1, %2" : "=v"(r) : "v"(lo), "v"(hi)); return r; }
;     __device__ __forceinline__ void operator()(const f32x4 (&acc)[2][2][4][2], const Unit& u, int wr, int wc, int fr, int fq) const {
;     ...
;             for (int m = 0; m < 4; ++m) { const int row = row0 + ai * HALF + m * 16; const size_t off = (size_t)row * 2048 + col0; float sq = 0.f;
; #pragma unroll
;                 for (int bj = 0; bj < 2; ++bj) { const u32x4 r = rb[m][bj];
;                     const f32x4 b0 = (f32x4){__builtin_bit_cast(float, r.x << 16), __builtin_bit_cast(float, r.x & 0xffff0000u), __builtin_bit_cast(float, r.y << 16), __builtin_bit_cast(float, r.y & 0xffff0000u)};
;                     const f32x4 b1 = (f32x4){__builtin_bit_cast(float, r.z << 16), __builtin_bit_cast(float, r.z & 0xffff0000u), __builtin_bit_cast(float, r.w << 16), __builtin_bit_cast(float, r.w & 0xffff0000u)};
;                     const f32x4 o0 = b0 + acc[ai][bj][m][0] * alpha, o1 = b1 + acc[ai][bj][m][1] * alpha;
;                     if (wf) { *(f32x4*)(fout + off + bj * HALF) = o0; *(f32x4*)(fout + off + bj * HALF + 4) = o1; }
;                     sq += (o0[0] * o0[0] + o0[1] * o0[1]) + (o0[2] * o0[2] + o0[3] * o0[3]) + (o1[0] * o1[0] + o1[1] * o1[1]) + (o1[2] * o1[2] + o1[3] * o1[3]);
;                     u32x4 w; w.x = cvt_pk_bf16(o0[0], o0[1]); w.y = cvt_pk_bf16(o0[2], o0[3]); w.z = cvt_pk_bf16(o1[0], o1[1]); w.w = cvt_pk_bf16(o1[2], o1[3]);
;                     *(u32x4*)(xb + off + bj * HALF) = w; }
.LBB0_321:
	s_or_b64 exec, exec, s[30:31]
	v_lshlrev_b64 v[16:17], 11, v[92:93]
	v_lshl_add_u64 v[18:19], v[16:17], 0, v[170:171]
	s_nop 0
	v_lshlrev_b32_e32 v20, 16, v228
	v_and_b32_e32 v21, 0xffff0000, v228
	v_lshlrev_b32_e32 v22, 16, v229
	v_and_b32_e32 v23, 0xffff0000, v229
	v_lshlrev_b32_e32 v24, 16, v230
	v_and_b32_e32 v25, 0xffff0000, v230
	v_lshlrev_b32_e32 v26, 16, v231
	v_and_b32_e32 v27, 0xffff0000, v231
	v_pk_fma_f32 v[14:15], v[14:15], 0.5, v[22:23] op_sel_hi:[1,0,1]
	v_pk_fma_f32 v[12:13], v[12:13], 0.5, v[20:21] op_sel_hi:[1,0,1]
	v_pk_fma_f32 v[10:11], v[10:11], 0.5, v[26:27] op_sel_hi:[1,0,1]
	v_pk_fma_f32 v[8:9], v[8:9], 0.5, v[24:25] op_sel_hi:[1,0,1]
	s_and_b64 vcc, exec, s[10:11]
	v_lshl_add_u64 v[18:19], v[18:19], 2, s[12:13]
	s_cbranch_vccnz .LBB0_323
	global_store_dwordx4 v[18:19], v[12:15], off
	global_store_dwordx4 v[18:19], v[8:11], off offset:16
.LBB0_323:
	v_cvt_pk_bf16_f32 v20, v12, v13
	v_cvt_pk_bf16_f32 v21, v14, v15
	v_cvt_pk_bf16_f32 v22, v8, v9
	v_cvt_pk_bf16_f32 v23, v10, v11
	v_lshl_add_u64 v[16:17], v[16:17], 1, v[168:169]
	global_store_dwordx4 v[16:17], v[20:23], off
	s_nop 0
	v_lshlrev_b32_e32 v24, 16, v234
	v_and_b32_e32 v25, 0xffff0000, v234
	v_lshlrev_b32_e32 v20, 16, v232
	v_and_b32_e32 v21, 0xffff0000, v232
	v_lshlrev_b32_e32 v22, 16, v233
	v_and_b32_e32 v23, 0xffff0000, v233
	v_lshlrev_b32_e32 v26, 16, v235
	v_and_b32_e32 v27, 0xffff0000, v235
	v_pk_fma_f32 v[6:7], v[6:7], 0.5, v[22:23] op_sel_hi:[1,0,1]
	v_pk_fma_f32 v[4:5], v[4:5], 0.5, v[20:21] op_sel_hi:[1,0,1]
	v_pk_fma_f32 v[2:3], v[2:3], 0.5, v[26:27] op_sel_hi:[1,0,1]
	s_and_b64 vcc, exec, s[10:11]
	v_pk_fma_f32 v[0:1], v[0:1], 0.5, v[24:25] op_sel_hi:[1,0,1]
	s_cbranch_vccnz .LBB0_325
	global_store_dwordx4 v[18:19], v[4:7], off offset:512
	global_store_dwordx4 v[18:19], v[0:3], off offset:528

; __device__ __forceinline__ unsigned cvt_pk_bf16(float lo, float hi) { unsigned r; asm volatile("v_cvt_pk_bf16_f32 %0, %1, %2" : "=v"(r) : "v"(lo), "v"(hi)); return r; }
; __device__ __forceinline__ float sum_fq(float s) { return sum_xor32(sum_xor16(s)); }
;     __device__ __forceinline__ void operator()(const f32x4 (&acc)[2][2][4][2], const Unit& u, int wr, int wc, int fr, int fq) const {
;     ...
;             for (int m = 0; m < 4; ++m) { const size_t off = (size_t)(row0 + ai * HALF + m * 16) * 2048 + col0;
; #pragma unroll
;                 for (int bj = 0; bj < 2; ++bj) rb[m][bj] = *(const u32x4*)(xb + off + bj * HALF); }
;             __builtin_amdgcn_sched_barrier(0);
; #pragma unroll
;             for (int m = 0; m < 4; ++m) { const int row = row0 + ai * HALF + m * 16; const size_t off = (size_t)row * 2048 + col0; float sq = 0.f;
; #pragma unroll
;                 for (int bj = 0; bj < 2; ++bj) { const u32x4 r = rb[m][bj];
;                     const f32x4 b0 = (f32x4){__builtin_bit_cast(float, r.x << 16), __builtin_bit_cast(float, r.x & 0xffff0000u), __builtin_bit_cast(float, r.y << 16), __builtin_bit_cast(float, r.y & 0xffff0000u)};
;                     const f32x4 b1 = (f32x4){__builtin_bit_cast(float, r.z << 16), __builtin_bit_cast(float, r.z & 0xffff0000u), __builtin_bit_cast(float, r.w << 16), __builtin_bit_cast(float, r.w & 0xffff0000u)};
;                     const f32x4 o0 = b0 + acc[ai][bj][m][0] * alpha, o1 = b1 + acc[ai][bj][m][1] * alpha;
;                     if (wf) { *(f32x4*)(fout + off + bj * HALF) = o0; *(f32x4*)(fout + off + bj * HALF + 4) = o1; }
;                     sq += (o0[0] * o0[0] + o0[1] * o0[1]) + (o0[2] * o0[2] + o0[3] * o0[3]) + (o1[0] * o1[0] + o1[1] * o1[1]) + (o1[2] * o1[2] + o1[3] * o1[3]);
;                     u32x4 w; w.x = cvt_pk_bf16(o0[0], o0[1]); w.y = cvt_pk_bf16(o0[2], o0[3]); w.z = cvt_pk_bf16(o1[0], o1[1]); w.w = cvt_pk_bf16(o1[2], o1[3]);
;                     *(u32x4*)(xb + off + bj * HALF) = w; }
;                 sq = sum_fq(sq);
;                 if (fq == 0) ssq[(size_t)row * 32 + u.pn * 4 + wc] = sq; }
.LBB0_661:
	s_or_b64 exec, exec, s[30:31]
	v_add_u32_e32 v100, 0x80, v164
	v_ashrrev_i32_e32 v101, 31, v100
	v_add_u32_e32 v96, 0x90, v164
	v_lshlrev_b64 v[110:111], 12, v[100:101]
	v_ashrrev_i32_e32 v97, 31, v96
	v_add_u32_e32 v92, 0xa0, v164
	v_lshl_add_u64 v[64:65], v[166:167], 0, v[110:111]
	v_lshlrev_b64 v[98:99], 12, v[96:97]
	v_ashrrev_i32_e32 v93, 31, v92
	v_add_u32_e32 v88, 0xb0, v164
	v_lshl_add_u64 v[64:65], v[166:167], 0, v[98:99]
	v_lshlrev_b64 v[94:95], 12, v[92:93]
	v_ashrrev_i32_e32 v89, 31, v88
	v_lshl_add_u64 v[64:65], v[166:167], 0, v[94:95]
	v_lshlrev_b64 v[90:91], 12, v[88:89]
	v_lshl_add_u64 v[64:65], v[166:167], 0, v[90:91]
	s_waitcnt vmcnt(8)
	v_lshlrev_b32_e32 v112, 16, v202
	v_and_b32_e32 v113, 0xffff0000, v202
	v_lshlrev_b32_e32 v102, 16, v203
	v_and_b32_e32 v103, 0xffff0000, v203
	v_lshlrev_b32_e32 v114, 16, v204
	v_and_b32_e32 v115, 0xffff0000, v204
	v_lshlrev_b32_e32 v104, 16, v205
	v_and_b32_e32 v105, 0xffff0000, v205
	v_pk_add_f32 v[62:63], v[62:63], v[102:103]
	v_pk_add_f32 v[60:61], v[60:61], v[112:113]
	v_pk_add_f32 v[102:103], v[58:59], v[104:105]
	v_pk_add_f32 v[58:59], v[56:57], v[114:115]
	v_mul_f32_e32 v56, v61, v61
	v_mul_f32_e32 v57, v63, v63
	v_fmac_f32_e32 v56, v60, v60
	v_fmac_f32_e32 v57, v62, v62
	v_add_f32_e32 v56, v56, v57
	v_mul_f32_e32 v57, v59, v59
	v_fmac_f32_e32 v57, v58, v58
	v_add_f32_e32 v56, v57, v56
	v_mul_f32_e32 v57, v103, v103
	v_fmac_f32_e32 v57, v102, v102
	v_add_f32_e32 v104, v57, v56
	v_cvt_pk_bf16_f32 v56, v60, v61
	v_lshl_add_u64 v[60:61], s[16:17], 0, v[110:111]
	v_cvt_pk_bf16_f32 v57, v62, v63
	v_cvt_pk_bf16_f32 v58, v58, v59
	v_cvt_pk_bf16_f32 v59, v102, v103
	v_lshl_add_u64 v[60:61], v[162:163], 1, v[60:61]
	global_store_dwordx4 v[60:61], v[56:59], off
	s_nop 0
	v_lshlrev_b32_e32 v62, 16, v208
	v_and_b32_e32 v63, 0xffff0000, v208
	v_lshlrev_b32_e32 v56, 16, v206
	v_and_b32_e32 v57, 0xffff0000, v206
	v_lshlrev_b32_e32 v58, 16, v207
	v_and_b32_e32 v59, 0xffff0000, v207
	v_lshlrev_b32_e32 v102, 16, v209
	v_and_b32_e32 v103, 0xffff0000, v209
	v_pk_add_f32 v[54:55], v[54:55], v[58:59]
	v_pk_add_f32 v[52:53], v[52:53], v[56:57]
	v_pk_add_f32 v[56:57], v[50:51], v[102:103]
	v_pk_add_f32 v[50:51], v[48:49], v[62:63]
	v_mul_f32_e32 v48, v53, v53
	v_mul_f32_e32 v49, v55, v55
	v_fmac_f32_e32 v48, v52, v52
	v_fmac_f32_e32 v49, v54, v54
	v_add_f32_e32 v48, v48, v49
	v_mul_f32_e32 v49, v51, v51
	v_fmac_f32_e32 v49, v50, v50
	v_add_f32_e32 v48, v49, v48
	v_mul_f32_e32 v49, v57, v57
	v_fmac_f32_e32 v49, v56, v56
	v_add_f32_e32 v48, v49, v48
	v_add_f32_e32 v58, v104, v48
	v_cvt_pk_bf16_f32 v48, v52, v53
	v_cvt_pk_bf16_f32 v49, v54, v55
	v_cvt_pk_bf16_f32 v50, v50, v51
	v_cvt_pk_bf16_f32 v51, v56, v57
	global_store_dwordx4 v[60:61], v[48:51], off offset:256
	s_nop 1
	v_mov_b32_e32 v48, v58
	s_nop 1
	v_permlane16_swap_b32 v48, v58
	s_nop 0
	v_add_f32_e32 v48, v48, v58
	v_mov_b32_e32 v49, v48
	s_nop 1
	v_permlane32_swap_b32 v48, v49
	s_and_saveexec_b64 s[30:31], s[4:5]
	s_cbranch_execz .LBB0_663
	v_lshlrev_b64 v[50:51], 7, v[100:101]
	v_lshl_add_u64 v[50:51], s[20:21], 0, v[50:51]
	v_lshl_add_u64 v[50:51], s[28:29], 2, v[50:51]
	s_lshl_b32 s36, s38, 2
	s_mov_b32 s37, s24
	v_lshl_add_u64 v[50:51], v[50:51], 0, s[36:37]
	v_add_f32_e32 v48, v48, v49
	global_store_dword v[50:51], v48, off
.LBB0_663:
	s_or_b64 exec, exec, s[30:31]
	s_nop 0
	v_lshlrev_b32_e32 v48, 16, v210
	v_and_b32_e32 v49, 0xffff0000, v210
	v_lshlrev_b32_e32 v50, 16, v211
	v_and_b32_e32 v51, 0xffff0000, v211
	v_lshlrev_b32_e32 v52, 16, v212
	v_and_b32_e32 v53, 0xffff0000, v212
	v_lshlrev_b32_e32 v54, 16, v213
	v_and_b32_e32 v55, 0xffff0000, v213
	v_pk_add_f32 v[46:47], v[46:47], v[50:51]
	v_pk_add_f32 v[44:45], v[44:45], v[48:49]
	v_pk_add_f32 v[48:49], v[42:43], v[54:55]
	v_pk_add_f32 v[42:43], v[40:41], v[52:53]
	v_mul_f32_e32 v40, v45, v45
	v_mul_f32_e32 v41, v47, v47
	v_fmac_f32_e32 v40, v44, v44
	v_fmac_f32_e32 v41, v46, v46
	v_add_f32_e32 v40, v40, v41
	v_mul_f32_e32 v41, v43, v43
	v_fmac_f32_e32 v41, v42, v42
	v_add_f32_e32 v40, v41, v40
	v_mul_f32_e32 v41, v49, v49
	v_fmac_f32_e32 v41, v48, v48
	v_add_f32_e32 v50, v41, v40
	v_cvt_pk_bf16_f32 v40, v44, v45
	v_lshl_add_u64 v[44:45], s[16:17], 0, v[98:99]
	v_cvt_pk_bf16_f32 v41, v46, v47
	v_cvt_pk_bf16_f32 v42, v42, v43
	v_cvt_pk_bf16_f32 v43, v48, v49
	v_lshl_add_u64 v[44:45], v[162:163], 1, v[44:45]
	global_store_dwordx4 v[44:45], v[40:43], off
	s_nop 0
	v_lshlrev_b32_e32 v46, 16, v216
	v_and_b32_e32 v47, 0xffff0000, v216
	v_lshlrev_b32_e32 v40, 16, v214
	v_and_b32_e32 v41, 0xffff0000, v214
	v_lshlrev_b32_e32 v42, 16, v215
	v_and_b32_e32 v43, 0xffff0000, v215
	v_lshlrev_b32_e32 v48, 16, v217
	v_and_b32_e32 v49, 0xffff0000, v217
	v_pk_add_f32 v[38:39], v[38:39], v[42:43]
	v_pk_add_f32 v[36:37], v[36:37], v[40:41]
	v_pk_add_f32 v[40:41], v[34:35], v[48:49]
	v_pk_add_f32 v[34:35], v[32:33], v[46:47]
	v_mul_f32_e32 v32, v37, v37
	v_mul_f32_e32 v33, v39, v39
	v_fmac_f32_e32 v32, v36, v36
	v_fmac_f32_e32 v33, v38, v38
	v_add_f32_e32 v32, v32, v33
	v_mul_f32_e32 v33, v35, v35
	v_fmac_f32_e32 v33, v34, v34
	v_add_f32_e32 v32, v33, v32
	v_mul_f32_e32 v33, v41, v41
	v_fmac_f32_e32 v33, v40, v40
	v_add_f32_e32 v32, v33, v32
	v_add_f32_e32 v42, v50, v32
	v_cvt_pk_bf16_f32 v32, v36, v37
	v_cvt_pk_bf16_f32 v33, v38, v39
	v_cvt_pk_bf16_f32 v34, v34, v35
	v_cvt_pk_bf16_f32 v35, v40, v41
	global_store_dwordx4 v[44:45], v[32:35], off offset:256
	s_nop 1
	v_mov_b32_e32 v32, v42
	s_nop 1
	v_permlane16_swap_b32 v42, v32
	s_nop 0
	v_add_f32_e32 v32, v42, v32
	v_mov_b32_e32 v33, v32
	s_nop 1
	v_permlane32_swap_b32 v33, v32
	s_and_saveexec_b64 s[30:31], s[4:5]
	s_cbranch_execz .LBB0_665
	v_lshlrev_b64 v[34:35], 7, v[96:97]
	v_lshl_add_u64 v[34:35], s[20:21], 0, v[34:35]
	v_lshl_add_u64 v[34:35], s[28:29], 2, v[34:35]
	s_lshl_b32 s36, s38, 2
	s_mov_b32 s37, s24
	v_lshl_add_u64 v[34:35], v[34:35], 0, s[36:37]
	v_add_f32_e32 v32, v33, v32
	global_store_dword v[34:35], v32, off
; __device__ __forceinline__ unsigned cvt_pk_bf16(float lo, float hi) { unsigned r; asm volatile("v_cvt_pk_bf16_f32 %0, %1, %2" : "=v"(r) : "v"(lo), "v"(hi)); return r; }
; __device__ __forceinline__ float sum_fq(float s) { return sum_xor32(sum_xor16(s)); }
;     __device__ __forceinline__ void operator()(const f32x4 (&acc)[2][2][4][2], const Unit& u, int wr, int wc, int fr, int fq) const {
;     ...
;             for (int m = 0; m < 4; ++m) { const int row = row0 + ai * HALF + m * 16; const size_t off = (size_t)row * 2048 + col0; float sq = 0.f;
; #pragma unroll
;                 for (int bj = 0; bj < 2; ++bj) { const u32x4 r = rb[m][bj];
;                     const f32x4 b0 = (f32x4){__builtin_bit_cast(float, r.x << 16), __builtin_bit_cast(float, r.x & 0xffff0000u), __builtin_bit_cast(float, r.y << 16), __builtin_bit_cast(float, r.y & 0xffff0000u)};
;                     const f32x4 b1 = (f32x4){__builtin_bit_cast(float, r.z << 16), __builtin_bit_cast(float, r.z & 0xffff0000u), __builtin_bit_cast(float, r.w << 16), __builtin_bit_cast(float, r.w & 0xffff0000u)};
;                     const f32x4 o0 = b0 + acc[ai][bj][m][0] * alpha, o1 = b1 + acc[ai][bj][m][1] * alpha;
;                     if (wf) { *(f32x4*)(fout + off + bj * HALF) = o0; *(f32x4*)(fout + off + bj * HALF + 4) = o1; }
;                     sq += (o0[0] * o0[0] + o0[1] * o0[1]) + (o0[2] * o0[2] + o0[3] * o0[3]) + (o1[0] * o1[0] + o1[1] * o1[1]) + (o1[2] * o1[2] + o1[3] * o1[3]);
;                     u32x4 w; w.x = cvt_pk_bf16(o0[0], o0[1]); w.y = cvt_pk_bf16(o0[2], o0[3]); w.z = cvt_pk_bf16(o1[0], o1[1]); w.w = cvt_pk_bf16(o1[2], o1[3]);
;                     *(u32x4*)(xb + off + bj * HALF) = w; }
;                 sq = sum_fq(sq);
;                 if (fq == 0) ssq[(size_t)row * 32 + u.pn * 4 + wc] = sq; }
.LBB0_665:
	s_or_b64 exec, exec, s[30:31]
	s_nop 0
	v_lshlrev_b32_e32 v32, 16, v222
	v_and_b32_e32 v33, 0xffff0000, v222
	v_lshlrev_b32_e32 v34, 16, v223
	v_and_b32_e32 v35, 0xffff0000, v223
	v_lshlrev_b32_e32 v36, 16, v224
	v_and_b32_e32 v37, 0xffff0000, v224
	v_lshlrev_b32_e32 v38, 16, v225
	v_and_b32_e32 v39, 0xffff0000, v225
	v_pk_add_f32 v[30:31], v[30:31], v[34:35]
	v_pk_add_f32 v[28:29], v[28:29], v[32:33]
	v_pk_add_f32 v[32:33], v[26:27], v[38:39]
	v_pk_add_f32 v[26:27], v[24:25], v[36:37]
	v_mul_f32_e32 v24, v29, v29
	v_mul_f32_e32 v25, v31, v31
	v_fmac_f32_e32 v24, v28, v28
	v_fmac_f32_e32 v25, v30, v30
	v_add_f32_e32 v24, v24, v25
	v_mul_f32_e32 v25, v27, v27
	v_fmac_f32_e32 v25, v26, v26
	v_add_f32_e32 v24, v25, v24
	v_mul_f32_e32 v25, v33, v33
	v_fmac_f32_e32 v25, v32, v32
	v_add_f32_e32 v34, v25, v24
	v_cvt_pk_bf16_f32 v24, v28, v29
	v_lshl_add_u64 v[28:29], s[16:17], 0, v[94:95]
	v_cvt_pk_bf16_f32 v25, v30, v31
	v_cvt_pk_bf16_f32 v26, v26, v27
	v_cvt_pk_bf16_f32 v27, v32, v33
	v_lshl_add_u64 v[28:29], v[162:163], 1, v[28:29]
	global_store_dwordx4 v[28:29], v[24:27], off
	s_nop 0
	v_lshlrev_b32_e32 v30, 16, v230
	v_and_b32_e32 v31, 0xffff0000, v230
	v_lshlrev_b32_e32 v24, 16, v228
	v_and_b32_e32 v25, 0xffff0000, v228
	v_lshlrev_b32_e32 v26, 16, v229
	v_and_b32_e32 v27, 0xffff0000, v229
	v_lshlrev_b32_e32 v32, 16, v231
	v_and_b32_e32 v33, 0xffff0000, v231
	v_pk_add_f32 v[22:23], v[22:23], v[26:27]
	v_pk_add_f32 v[20:21], v[20:21], v[24:25]
	v_pk_add_f32 v[24:25], v[18:19], v[32:33]
	v_pk_add_f32 v[18:19], v[16:17], v[30:31]
	v_mul_f32_e32 v16, v21, v21
	v_mul_f32_e32 v17, v23, v23
	v_fmac_f32_e32 v16, v20, v20
	v_fmac_f32_e32 v17, v22, v22
	v_add_f32_e32 v16, v16, v17
	v_mul_f32_e32 v17, v19, v19
	v_fmac_f32_e32 v17, v18, v18
	v_add_f32_e32 v16, v17, v16
	v_mul_f32_e32 v17, v25, v25
	v_fmac_f32_e32 v17, v24, v24
	v_add_f32_e32 v16, v17, v16
	v_add_f32_e32 v26, v34, v16
	v_cvt_pk_bf16_f32 v16, v20, v21
	v_cvt_pk_bf16_f32 v17, v22, v23
	v_cvt_pk_bf16_f32 v18, v18, v19
	v_cvt_pk_bf16_f32 v19, v24, v25
	global_store_dwordx4 v[28:29], v[16:19], off offset:256
	s_nop 1
	v_mov_b32_e32 v16, v26
	s_nop 1
	v_permlane16_swap_b32 v16, v26
	s_nop 0
	v_add_f32_e32 v16, v16, v26
	v_mov_b32_e32 v17, v16
	s_nop 1
	v_permlane32_swap_b32 v16, v17
	s_and_saveexec_b64 s[30:31], s[4:5]
	s_cbranch_execz .LBB0_667
	v_lshlrev_b64 v[18:19], 7, v[92:93]
	v_lshl_add_u64 v[18:19], s[20:21], 0, v[18:19]
	v_lshl_add_u64 v[18:19], s[28:29], 2, v[18:19]
	s_lshl_b32 s36, s38, 2
	s_mov_b32 s37, s24
	v_lshl_add_u64 v[18:19], v[18:19], 0, s[36:37]
	v_add_f32_e32 v16, v16, v17
	global_store_dword v[18:19], v16, off
.LBB0_667:
	s_or_b64 exec, exec, s[30:31]
	s_nop 0
	v_lshlrev_b32_e32 v16, 16, v232
	v_and_b32_e32 v17, 0xffff0000, v232
	v_lshlrev_b32_e32 v18, 16, v233
	v_and_b32_e32 v19, 0xffff0000, v233
	v_lshlrev_b32_e32 v20, 16, v234
	v_and_b32_e32 v21, 0xffff0000, v234
	v_lshlrev_b32_e32 v22, 16, v235
	v_and_b32_e32 v23, 0xffff0000, v235
	v_pk_add_f32 v[14:15], v[14:15], v[18:19]
	v_pk_add_f32 v[12:13], v[12:13], v[16:17]
	v_pk_add_f32 v[16:17], v[10:11], v[22:23]
	v_pk_add_f32 v[10:11], v[8:9], v[20:21]
	v_mul_f32_e32 v8, v13, v13
	v_mul_f32_e32 v9, v15, v15
	v_fmac_f32_e32 v8, v12, v12
	v_fmac_f32_e32 v9, v14, v14
	v_add_f32_e32 v8, v8, v9
	v_mul_f32_e32 v9, v11, v11
	v_fmac_f32_e32 v9, v10, v10
	v_add_f32_e32 v8, v9, v8
	v_mul_f32_e32 v9, v17, v17
	v_fmac_f32_e32 v9, v16, v16
	v_add_f32_e32 v18, v9, v8
	v_cvt_pk_bf16_f32 v8, v12, v13
	v_lshl_add_u64 v[12:13], s[16:17], 0, v[90:91]
	v_cvt_pk_bf16_f32 v9, v14, v15
	v_cvt_pk_bf16_f32 v10, v10, v11
	v_cvt_pk_bf16_f32 v11, v16, v17
	v_lshl_add_u64 v[12:13], v[162:163], 1, v[12:13]
	global_store_dwordx4 v[12:13], v[8:11], off
	s_nop 0
	v_lshlrev_b32_e32 v14, 16, v238
	v_and_b32_e32 v15, 0xffff0000, v238
	v_lshlrev_b32_e32 v8, 16, v236
	v_and_b32_e32 v9, 0xffff0000, v236
	v_lshlrev_b32_e32 v10, 16, v237
	v_and_b32_e32 v11, 0xffff0000, v237
	v_lshlrev_b32_e32 v16, 16, v239
	v_and_b32_e32 v17, 0xffff0000, v239
	v_pk_add_f32 v[6:7], v[6:7], v[10:11]
	v_pk_add_f32 v[4:5], v[4:5], v[8:9]
	v_pk_add_f32 v[8:9], v[2:3], v[16:17]
	v_pk_add_f32 v[2:3], v[0:1], v[14:15]
	v_mul_f32_e32 v0, v5, v5
	v_mul_f32_e32 v1, v7, v7
	v_fmac_f32_e32 v0, v4, v4
	v_fmac_f32_e32 v1, v6, v6
	v_add_f32_e32 v0, v0, v1
	v_mul_f32_e32 v1, v3, v3
	v_fmac_f32_e32 v1, v2, v2
	v_add_f32_e32 v0, v1, v0
	v_mul_f32_e32 v1, v9, v9
	v_fmac_f32_e32 v1, v8, v8
	v_add_f32_e32 v0, v1, v0
	v_add_f32_e32 v10, v18, v0
	v_cvt_pk_bf16_f32 v0, v4, v5
	v_cvt_pk_bf16_f32 v1, v6, v7
	v_cvt_pk_bf16_f32 v2, v2, v3
	v_cvt_pk_bf16_f32 v3, v8, v9
	global_store_dwordx4 v[12:13], v[0:3], off offset:256
	s_nop 1
	v_mov_b32_e32 v0, v10
	s_nop 1
	v_permlane16_swap_b32 v10, v0
	s_nop 0
	v_add_f32_e32 v0, v10, v0
	v_mov_b32_e32 v1, v0
	s_nop 1
	v_permlane32_swap_b32 v1, v0
	s_and_saveexec_b64 s[30:31], s[4:5]
	s_cbranch_execz .LBB0_669
	v_lshlrev_b64 v[2:3], 7, v[88:89]
	v_lshl_add_u64 v[2:3], s[20:21], 0, v[2:3]
	v_lshl_add_u64 v[2:3], s[28:29], 2, v[2:3]
	s_lshl_b32 s28, s38, 2
	s_mov_b32 s29, s24
	v_lshl_add_u64 v[2:3], v[2:3], 0, s[28:29]
	v_add_f32_e32 v0, v1, v0
	global_store_dword v[2:3], v0, off
